# diff fast path without max-subtract (fallback to general), phase D epilogue load hoist, X-chain trim
# speedup vs baseline: 1.0585x; 1.0338x over previous
.LBB0_457:
	v_readlane_b32 s2, v254, 36
	s_add_i32 s7, s6, s2
	s_cmpk_gt_i32 s7, 0x7ff
	s_mov_b64 s[4:5], -1
	s_cbranch_scc1 .LBB0_456
	v_readlane_b32 s2, v253, 51
	v_readlane_b32 s4, v253, 49
	s_add_i32 s8, s6, s2
	s_ashr_i32 s9, s7, 5
	v_readlane_b32 s5, v253, 50
	s_and_b64 s[4:5], s[4:5], exec
	s_cselect_b32 s4, s85, s7
	s_cselect_b32 s5, s8, s9
	s_lshl_b32 s4, s4, 7
	s_and_b32 s16, s4, 0xf80
	s_lshl_b32 s4, s5, 7
	s_ashr_i32 s7, s5, 3
	s_and_b32 s8, s4, 0x380
	s_lshl_b32 s9, s7, 12
	s_lshl_b32 s10, s7, 8
	s_lshr_b32 s7, s8, 6
	s_add_i32 s10, s10, 0x8000
	s_mul_i32 s11, s7, 0x8800
	s_ashr_i32 s17, s9, 31
	v_mbcnt_lo_u32_b32 v0, -1, 0
	v_mbcnt_hi_u32_b32 v0, -1, v0
	s_add_u32 s4, s11, s9
	v_add_u32_e32 v187, s69, v0
	s_addc_u32 s5, 0, s17
	v_and_b32_e32 v0, 7, v187
	v_bfe_u32 v188, v187, 4, 2
	v_bitop3_b32 v0, v188, v0, s83 bitop3:0x36
	s_lshl_b64 s[4:5], s[4:5], 7
	v_and_or_b32 v0, v187, 56, v0
	s_add_u32 s12, s95, s4
	v_lshl_or_b32 v212, v0, 4, s46
	s_addc_u32 s13, s3, s5
	s_mov_b32 s19, m0
	s_mov_b32 m0, s23
	s_nop 0
	global_load_lds_dwordx4 v212, s[12:13]
	s_mov_b32 m0, s19
	s_add_i32 s12, s11, 0x8800
	s_add_u32 s28, s12, s9
	s_addc_u32 s29, 0, s17
	s_lshl_b64 s[28:29], s[28:29], 7
	v_bfe_u32 v5, v187, 5, 1
	v_lshlrev_b32_e32 v190, 4, v187
	s_add_u32 s28, s95, s28
	v_or_b32_e32 v2, s25, v5
	v_and_b32_e32 v3, 0x1c0, v190
	v_lshlrev_b32_e32 v189, 3, v187
	s_addc_u32 s29, s3, s29
	s_add_i32 s13, s23, 0x2000
	v_lshl_or_b32 v2, v2, 9, v3
	v_and_b32_e32 v6, 24, v189
	v_readlane_b32 s2, v253, 62
	s_add_u32 s4, s14, s4
	s_mov_b32 s17, m0
	s_mov_b32 m0, s13
	s_nop 0
	global_load_lds_dwordx4 v212, s[28:29]
	s_mov_b32 m0, s17
	s_addc_u32 s5, s15, s5
	v_or3_b32 v2, v2, s2, v6
	v_readlane_b32 s2, v253, 63
	s_add_i32 s13, s23, 0x4000
	v_and_b32_e32 v191, 31, v187
	v_add_lshl_u32 v222, v2, s2, 1
	s_mov_b32 s17, m0
	s_mov_b32 m0, s13
	s_nop 0
	global_load_lds_dwordx4 v222, s[4:5]
	s_mov_b32 m0, s17
	v_readlane_b32 s2, v254, 26
	s_add_i32 s13, s23, 0x6000
	v_lshlrev_b32_e32 v0, 4, v5
	v_add_lshl_u32 v223, v2, s2, 1
	s_mov_b32 s17, m0
	s_mov_b32 m0, s13
	s_nop 0
	global_load_lds_dwordx4 v223, s[4:5]
	s_mov_b32 m0, s17
	s_or_b32 s13, s9, 64
	s_ashr_i32 s17, s13, 31
	s_add_u32 s4, s11, s13
	s_addc_u32 s5, 0, s17
	s_lshl_b64 s[4:5], s[4:5], 7
	s_add_u32 s28, s95, s4
	s_addc_u32 s29, s3, s5
	s_add_i32 s19, s23, 0x8000
	s_mov_b32 s20, m0
	s_mov_b32 m0, s19
	s_nop 0
	global_load_lds_dwordx4 v212, s[28:29]
	s_mov_b32 m0, s20
	s_add_u32 s28, s12, s13
	s_addc_u32 s29, 0, s17
	s_lshl_b64 s[28:29], s[28:29], 7
	s_add_u32 s28, s95, s28
	s_addc_u32 s29, s3, s29
	s_add_i32 s13, s23, 0xa000
	s_mov_b32 s17, m0
	s_mov_b32 m0, s13
	s_nop 0
	global_load_lds_dwordx4 v212, s[28:29]
	s_mov_b32 m0, s17
	s_add_u32 s4, s14, s4
	s_addc_u32 s5, s15, s5
	s_add_i32 s13, s23, 0xc000
	s_mov_b32 s17, m0
	s_mov_b32 m0, s13
	s_nop 0
	global_load_lds_dwordx4 v222, s[4:5]
	s_mov_b32 m0, s17
	v_readlane_b32 s2, v254, 33
	s_add_i32 s13, s23, 0xe000
	s_mov_b32 s17, m0
	s_mov_b32 m0, s13
	s_nop 0
	global_load_lds_dwordx4 v223, s[4:5]
	s_mov_b32 m0, s17
	s_add_i32 s4, s7, s2
	v_readlane_b32 s2, v253, 53
	s_or_b32 s5, s16, s2
	s_or_b32 s7, s5, s9
	v_or_b32_e32 v2, s7, v191
	v_ashrrev_i32_e32 v3, 31, v2
	v_mad_u64_u32 v[2:3], s[4:5], s4, v217, v[2:3]
	v_lshlrev_b64 v[2:3], 7, v[2:3]
	v_lshl_add_u64 v[2:3], s[58:59], 0, v[2:3]
	v_lshl_add_u64 v[2:3], v[2:3], 0, v[0:1]
	global_load_dwordx4 v[144:147], v[2:3], off offset:96
	global_load_dwordx4 v[148:151], v[2:3], off offset:64
	global_load_dwordx4 v[152:155], v[2:3], off offset:32
	global_load_dwordx4 v[156:159], v[2:3], off
	v_lshrrev_b32_e32 v0, 1, v187
	v_lshrrev_b32_e32 v7, 2, v187
	v_lshlrev_b32_e32 v193, 2, v5
	v_lshlrev_b32_e32 v8, 1, v187
	v_bfe_u32 v9, v187, 1, 3
	v_bitop3_b32 v0, v5, v0, 7 bitop3:0x78
	v_and_or_b32 v7, v7, 3, v193
	v_lshlrev_b32_e32 v192, 3, v5
	v_and_b32_e32 v8, 32, v8
	v_bitop3_b32 v10, v5, v9, 2 bitop3:0x36
	v_bitop3_b32 v11, v5, v9, 4 bitop3:0x36
	v_bitop3_b32 v5, v5, v9, 6 bitop3:0x36
	v_lshlrev_b32_e32 v228, 4, v0
	v_lshlrev_b32_e32 v0, 6, v7
	v_mov_b32_e32 v14, v1
	v_mov_b32_e32 v15, v1
	v_mov_b32_e32 v2, v1
	v_mov_b32_e32 v3, v1
	v_mov_b32_e32 v4, v1
	v_lshlrev_b32_e32 v226, 4, v10
	v_lshlrev_b32_e32 v225, 4, v11
	v_lshlrev_b32_e32 v224, 4, v5
	v_or3_b32 v210, v0, v8, v6
	v_mov_b32_e32 v0, v1
	v_mov_b32_e32 v5, v1
	v_mov_b32_e32 v6, v1
	v_mov_b32_e32 v7, v1
	v_mov_b32_e32 v8, v1
	v_mov_b32_e32 v9, v1
	v_mov_b32_e32 v10, v1
	v_mov_b32_e32 v11, v1
	v_mov_b32_e32 v12, v1
	v_mov_b32_e32 v13, v1
	v_mov_b64_e32 v[78:79], v[14:15]
	v_mov_b64_e32 v[62:63], v[14:15]
	v_mov_b64_e32 v[46:47], v[14:15]
	v_mov_b64_e32 v[30:31], v[14:15]
	v_mov_b64_e32 v[94:95], v[14:15]
	s_mov_b32 s13, 2
	s_mov_b32 s19, 0
	v_and_b32_e32 v194, 63, v187
	v_lshl_add_u32 v227, v191, 7, s21
	v_add_u32_e32 v195, 0, v210
	s_mov_b64 s[4:5], -1
	v_mov_b32_e32 v209, 0
	v_mov_b32_e32 v140, 0
	v_mov_b32_e32 v141, 0
	v_mov_b32_e32 v142, 0
	v_mov_b32_e32 v143, 0
	v_mov_b32_e32 v136, 0
	v_mov_b32_e32 v137, 0
	v_mov_b32_e32 v138, 0
	v_mov_b32_e32 v139, 0
	v_mov_b32_e32 v132, 0
	v_mov_b32_e32 v133, 0
	v_mov_b32_e32 v134, 0
	v_mov_b32_e32 v135, 0
	v_mov_b32_e32 v128, 0
	v_mov_b32_e32 v129, 0
	v_mov_b32_e32 v130, 0
	v_mov_b32_e32 v131, 0
	v_mov_b64_e32 v[76:77], v[12:13]
	v_mov_b64_e32 v[74:75], v[10:11]
	v_mov_b64_e32 v[72:73], v[8:9]
	v_mov_b64_e32 v[70:71], v[6:7]
	v_mov_b64_e32 v[68:69], v[4:5]
	v_mov_b64_e32 v[66:67], v[2:3]
	v_mov_b64_e32 v[64:65], v[0:1]
	v_mov_b64_e32 v[60:61], v[12:13]
	v_mov_b64_e32 v[58:59], v[10:11]
	v_mov_b64_e32 v[56:57], v[8:9]
	v_mov_b64_e32 v[54:55], v[6:7]
	v_mov_b64_e32 v[52:53], v[4:5]
	v_mov_b64_e32 v[50:51], v[2:3]
	v_mov_b64_e32 v[48:49], v[0:1]
	v_mov_b64_e32 v[44:45], v[12:13]
	v_mov_b64_e32 v[42:43], v[10:11]
	v_mov_b64_e32 v[40:41], v[8:9]
	v_mov_b64_e32 v[38:39], v[6:7]
	v_mov_b64_e32 v[36:37], v[4:5]
	v_mov_b64_e32 v[34:35], v[2:3]
	v_mov_b64_e32 v[32:33], v[0:1]
	v_mov_b64_e32 v[28:29], v[12:13]
	v_mov_b64_e32 v[26:27], v[10:11]
	v_mov_b64_e32 v[24:25], v[8:9]
	v_mov_b64_e32 v[22:23], v[6:7]
	v_mov_b64_e32 v[20:21], v[4:5]
	v_mov_b64_e32 v[18:19], v[2:3]
	v_mov_b64_e32 v[16:17], v[0:1]
	v_mov_b64_e32 v[92:93], v[12:13]
	v_mov_b64_e32 v[90:91], v[10:11]
	v_mov_b64_e32 v[88:89], v[8:9]
	v_mov_b64_e32 v[86:87], v[6:7]
	v_mov_b64_e32 v[84:85], v[4:5]
	v_mov_b64_e32 v[82:83], v[2:3]
	v_mov_b64_e32 v[80:81], v[0:1]
	s_mov_b32 s28, 0
	s_waitcnt vmcnt(0)
	s_branch .Lf_460

.Lf_to463:
	ds_read_b64_tr_b16 v[180:181], v0 offset:16384
	ds_read_b64_tr_b16 v[182:183], v0 offset:16896
	ds_read_b64_tr_b16 v[230:231], v0 offset:17408
	ds_read_b64_tr_b16 v[232:233], v0 offset:17920
	s_mov_b32 s62, s60
	s_mov_b32 s63, s60
	s_waitcnt lgkmcnt(2)
	v_mfma_f32_32x32x16_bf16 v[64:79], v[180:183], v[140:143], v[64:79]
	s_mov_b32 s61, s60
	v_max_f32_e32 v15, v14, v14
	v_max_f32_e32 v218, v209, v209
	v_max_f32_e32 v15, v218, v15
	v_cndmask_b32_e64 v15, v14, v15, s[4:5]
	v_sub_f32_e32 v14, v209, v15
	v_exp_f32_e32 v14, v14
	s_waitcnt lgkmcnt(0)
	v_mfma_f32_32x32x16_bf16 v[64:79], v[230:233], v[136:139], v[64:79]
	ds_read_b64_tr_b16 v[180:181], v0 offset:18432
	ds_read_b64_tr_b16 v[182:183], v0 offset:18944
	ds_read_b64_tr_b16 v[230:231], v0 offset:19456
	ds_read_b64_tr_b16 v[232:233], v0 offset:19968
	v_mov_b32_e32 v209, v15
	v_cndmask_b32_e64 v14, 0, v14, s[4:5]
	s_mov_b64 s[4:5], -1
	s_waitcnt lgkmcnt(2)
	v_mfma_f32_32x32x16_bf16 v[64:79], v[180:183], v[132:135], v[64:79]
	s_waitcnt lgkmcnt(0)
	v_mfma_f32_32x32x16_bf16 v[64:79], v[230:233], v[128:131], v[64:79]
	ds_read_b64_tr_b16 v[180:181], v0 offset:20480
	ds_read_b64_tr_b16 v[182:183], v0 offset:20992
	ds_read_b64_tr_b16 v[230:231], v0 offset:21504
	ds_read_b64_tr_b16 v[232:233], v0 offset:22016
	s_waitcnt lgkmcnt(2)
	v_mfma_f32_32x32x16_bf16 v[48:63], v[180:183], v[140:143], v[48:63]
	s_nop 5
	v_mul_f32_e64 v78, v14, v78
	v_mul_f32_e64 v79, v14, v79
	v_mul_f32_e64 v76, v14, v76
	v_mul_f32_e64 v77, v14, v77
	v_mul_f32_e64 v74, v14, v74
	v_mul_f32_e64 v75, v14, v75
	v_pk_mul_f32 v[72:73], v[14:15], v[72:73] op_sel_hi:[0,1]
	v_pk_mul_f32 v[70:71], v[14:15], v[70:71] op_sel_hi:[0,1]
	v_pk_mul_f32 v[68:69], v[14:15], v[68:69] op_sel_hi:[0,1]
	v_pk_mul_f32 v[66:67], v[14:15], v[66:67] op_sel_hi:[0,1]
	s_waitcnt lgkmcnt(0)
	v_mfma_f32_32x32x16_bf16 v[48:63], v[230:233], v[136:139], v[48:63]
	ds_read_b64_tr_b16 v[180:181], v0 offset:22528
	ds_read_b64_tr_b16 v[182:183], v0 offset:23040
	ds_read_b64_tr_b16 v[230:231], v0 offset:23552
	ds_read_b64_tr_b16 v[232:233], v0 offset:24064
	v_mul_f32_e64 v64, v14, v64
	v_mul_f32_e64 v65, v14, v65
	s_waitcnt lgkmcnt(2)
	v_mfma_f32_32x32x16_bf16 v[48:63], v[180:183], v[132:135], v[48:63]
	s_waitcnt lgkmcnt(0)
	v_mfma_f32_32x32x16_bf16 v[48:63], v[230:233], v[128:131], v[48:63]
	ds_read_b64_tr_b16 v[180:181], v0 offset:24576
	ds_read_b64_tr_b16 v[182:183], v0 offset:25088
	ds_read_b64_tr_b16 v[230:231], v0 offset:25600
	ds_read_b64_tr_b16 v[232:233], v0 offset:26112
	s_waitcnt lgkmcnt(2)
	v_mfma_f32_32x32x16_bf16 v[32:47], v[180:183], v[140:143], v[32:47]
	s_nop 5
	v_mul_f32_e64 v62, v14, v62
	v_mul_f32_e64 v63, v14, v63
	v_mul_f32_e64 v60, v14, v60
	v_mul_f32_e64 v61, v14, v61
	v_mul_f32_e64 v58, v14, v58
	v_mul_f32_e64 v59, v14, v59
	v_pk_mul_f32 v[56:57], v[14:15], v[56:57] op_sel_hi:[0,1]
	v_pk_mul_f32 v[54:55], v[14:15], v[54:55] op_sel_hi:[0,1]
	v_pk_mul_f32 v[52:53], v[14:15], v[52:53] op_sel_hi:[0,1]
	v_pk_mul_f32 v[50:51], v[14:15], v[50:51] op_sel_hi:[0,1]
	s_waitcnt lgkmcnt(0)
	v_mfma_f32_32x32x16_bf16 v[32:47], v[230:233], v[136:139], v[32:47]
	ds_read_b64_tr_b16 v[180:181], v0 offset:26624
	ds_read_b64_tr_b16 v[182:183], v0 offset:27136
	ds_read_b64_tr_b16 v[230:231], v0 offset:27648
	ds_read_b64_tr_b16 v[232:233], v0 offset:28160
	v_mul_f32_e64 v48, v14, v48
	v_mul_f32_e64 v49, v14, v49
	s_waitcnt lgkmcnt(2)
	v_mfma_f32_32x32x16_bf16 v[32:47], v[180:183], v[132:135], v[32:47]
	s_waitcnt lgkmcnt(0)
	v_mfma_f32_32x32x16_bf16 v[32:47], v[230:233], v[128:131], v[32:47]
	ds_read_b64_tr_b16 v[180:181], v0 offset:28672
	ds_read_b64_tr_b16 v[182:183], v0 offset:29184
	ds_read_b64_tr_b16 v[230:231], v0 offset:29696
	ds_read_b64_tr_b16 v[232:233], v0 offset:30208
	s_waitcnt lgkmcnt(2)
	v_mfma_f32_32x32x16_bf16 v[16:31], v[180:183], v[140:143], v[16:31]
	ds_read_b64_tr_b16 v[180:181], v0 offset:30720
	ds_read_b64_tr_b16 v[182:183], v0 offset:31232
	ds_read_b64_tr_b16 v[234:235], v0 offset:31744
	ds_read_b64_tr_b16 v[236:237], v0 offset:32256
	s_nop 1
	v_mul_f32_e64 v46, v14, v46
	v_mul_f32_e64 v47, v14, v47
	v_pk_mul_f32 v[44:45], v[14:15], v[44:45] op_sel_hi:[0,1]
	v_pk_mul_f32 v[42:43], v[14:15], v[42:43] op_sel_hi:[0,1]
	v_pk_mul_f32 v[40:41], v[14:15], v[40:41] op_sel_hi:[0,1]
	v_pk_mul_f32 v[38:39], v[14:15], v[38:39] op_sel_hi:[0,1]
	v_pk_mul_f32 v[36:37], v[14:15], v[36:37] op_sel_hi:[0,1]
	s_waitcnt lgkmcnt(4)
	v_mfma_f32_32x32x16_bf16 v[16:31], v[230:233], v[136:139], v[16:31]
	v_mul_f32_e64 v34, v14, v34
	v_mul_f32_e64 v35, v14, v35
	v_mul_f32_e64 v32, v14, v32
	v_mul_f32_e64 v33, v14, v33
	s_waitcnt lgkmcnt(2)
	v_mfma_f32_32x32x16_bf16 v[16:31], v[180:183], v[132:135], v[16:31]
	v_mov_b64_e32 v[182:183], s[62:63]
	v_mov_b64_e32 v[180:181], s[60:61]
	s_nop 1
	v_mfma_f32_32x32x16_bf16 v[80:95], v[180:183], v[140:143], v[80:95]
	v_mov_b32_e32 v140, 0
	v_mov_b32_e32 v141, v140
	v_mov_b32_e32 v142, v140
	v_mov_b32_e32 v143, v140
	v_mfma_f32_32x32x16_bf16 v[80:95], v[180:183], v[136:139], v[80:95]
	v_mov_b32_e32 v136, v140
	v_mov_b32_e32 v137, v140
	v_mov_b32_e32 v138, v140
	v_mov_b32_e32 v139, v140
	v_mfma_f32_32x32x16_bf16 v[80:95], v[180:183], v[132:135], v[80:95]
	v_mov_b32_e32 v132, v140
	v_mov_b32_e32 v133, v140
	v_mov_b32_e32 v134, v140
	v_mov_b32_e32 v135, v140
	s_waitcnt lgkmcnt(0)
	v_mfma_f32_32x32x16_bf16 v[16:31], v[234:237], v[128:131], v[16:31]
	v_mfma_f32_32x32x16_bf16 v[80:95], v[180:183], v[128:131], v[80:95]
	s_nop 10
	v_mul_f32_e64 v30, v14, v30
	v_mul_f32_e64 v31, v14, v31
	v_mul_f32_e64 v28, v14, v28
	v_mul_f32_e64 v29, v14, v29
	v_mul_f32_e64 v26, v14, v26
	v_mul_f32_e64 v27, v14, v27
	v_pk_mul_f32 v[24:25], v[14:15], v[24:25] op_sel_hi:[0,1]
	v_pk_mul_f32 v[22:23], v[14:15], v[22:23] op_sel_hi:[0,1]
	v_pk_mul_f32 v[20:21], v[14:15], v[20:21] op_sel_hi:[0,1]
	v_pk_mul_f32 v[18:19], v[14:15], v[18:19] op_sel_hi:[0,1]
	v_pk_mul_f32 v[16:17], v[14:15], v[16:17] op_sel_hi:[0,1]
	v_pk_mul_f32 v[94:95], v[14:15], v[94:95] op_sel_hi:[0,1]
	v_pk_mul_f32 v[92:93], v[14:15], v[92:93] op_sel_hi:[0,1]
	v_pk_mul_f32 v[90:91], v[14:15], v[90:91] op_sel_hi:[0,1]
	v_pk_mul_f32 v[88:89], v[14:15], v[88:89] op_sel_hi:[0,1]
	v_pk_mul_f32 v[86:87], v[14:15], v[86:87] op_sel_hi:[0,1]
	v_pk_mul_f32 v[84:85], v[14:15], v[84:85] op_sel_hi:[0,1]
	v_pk_mul_f32 v[82:83], v[14:15], v[82:83] op_sel_hi:[0,1]
	v_pk_mul_f32 v[80:81], v[14:15], v[80:81] op_sel_hi:[0,1]
	v_mov_b32_e32 v128, v140
	v_mov_b32_e32 v129, v140
	v_mov_b32_e32 v130, v140
	v_mov_b32_e32 v131, v140
	s_branch .LBB0_459
.Lf_459:
	v_mov_b32_e32 v180, v128
	v_mov_b32_e32 v181, v129
	v_mov_b32_e32 v182, v130
	v_mov_b32_e32 v183, v131
	v_mfma_f32_32x32x16_bf16 v[64:79], v[176:179], v[140:143], v[64:79]
	ds_read_b64_tr_b16 v[128:129], v0 offset:24576
	ds_read_b64_tr_b16 v[130:131], v0 offset:25088
	v_exp_f32_e32 v14, v112
	s_mov_b32 s61, s60
	s_mov_b32 s62, s60
	s_mov_b32 s63, s60
	v_mfma_f32_32x32x16_bf16 v[64:79], v[172:175], v[136:139], v[64:79]
	ds_read_b64_tr_b16 v[172:173], v0 offset:25600
	ds_read_b64_tr_b16 v[174:175], v0 offset:26112
	v_exp_f32_e32 v15, v96
	v_mfma_f32_32x32x16_bf16 v[64:79], v[168:171], v[132:135], v[64:79]
	ds_read_b64_tr_b16 v[168:169], v0 offset:26624
	ds_read_b64_tr_b16 v[170:171], v0 offset:27136
	v_exp_f32_e32 v96, v113
	v_mfma_f32_32x32x16_bf16 v[64:79], v[164:167], v[180:183], v[64:79]
	ds_read_b64_tr_b16 v[164:165], v0 offset:27648
	ds_read_b64_tr_b16 v[166:167], v0 offset:28160
	v_exp_f32_e32 v97, v97
	v_mfma_f32_32x32x16_bf16 v[48:63], v[160:163], v[140:143], v[48:63]
	ds_read_b64_tr_b16 v[160:161], v0 offset:28672
	ds_read_b64_tr_b16 v[162:163], v0 offset:29184
	v_exp_f32_e32 v112, v114
	v_mfma_f32_32x32x16_bf16 v[48:63], v[10:13], v[136:139], v[48:63]
	ds_read_b64_tr_b16 v[10:11], v0 offset:29696
	ds_read_b64_tr_b16 v[12:13], v0 offset:30208
	v_exp_f32_e32 v98, v98
	v_mfma_f32_32x32x16_bf16 v[48:63], v[6:9], v[132:135], v[48:63]
	ds_read_b64_tr_b16 v[6:7], v0 offset:30720
	ds_read_b64_tr_b16 v[8:9], v0 offset:31232
	v_exp_f32_e32 v113, v115
	v_mfma_f32_32x32x16_bf16 v[48:63], v[2:5], v[180:183], v[48:63]
	ds_read_b64_tr_b16 v[2:3], v0 offset:31744
	ds_read_b64_tr_b16 v[4:5], v0 offset:32256
	v_exp_f32_e32 v0, v99
	s_waitcnt lgkmcnt(14)
	v_mfma_f32_32x32x16_bf16 v[32:47], v[128:131], v[140:143], v[32:47]
	v_exp_f32_e32 v99, v116
	v_exp_f32_e32 v100, v100
	v_exp_f32_e32 v114, v117
	s_waitcnt lgkmcnt(12)
	v_mfma_f32_32x32x16_bf16 v[32:47], v[172:175], v[136:139], v[32:47]
	v_exp_f32_e32 v101, v101
	v_exp_f32_e32 v115, v118
	v_exp_f32_e32 v102, v102
	s_waitcnt lgkmcnt(10)
	v_mfma_f32_32x32x16_bf16 v[32:47], v[168:171], v[132:135], v[32:47]
	v_exp_f32_e32 v116, v119
	v_exp_f32_e32 v103, v103
	v_exp_f32_e32 v117, v120
	s_waitcnt lgkmcnt(8)
	v_mfma_f32_32x32x16_bf16 v[32:47], v[164:167], v[180:183], v[32:47]
	v_exp_f32_e32 v104, v104
	v_exp_f32_e32 v118, v121
	v_exp_f32_e32 v105, v105
	s_waitcnt lgkmcnt(6)
	v_mfma_f32_32x32x16_bf16 v[16:31], v[160:163], v[140:143], v[16:31]
	v_exp_f32_e32 v119, v122
	v_exp_f32_e32 v106, v106
	v_exp_f32_e32 v120, v123
	s_waitcnt lgkmcnt(4)
	v_mfma_f32_32x32x16_bf16 v[16:31], v[10:13], v[136:139], v[16:31]
	v_exp_f32_e32 v10, v107
	v_exp_f32_e32 v11, v124
	v_exp_f32_e32 v12, v108
	v_mov_b32_e32 v13, v118
	s_waitcnt lgkmcnt(2)
	v_mfma_f32_32x32x16_bf16 v[16:31], v[6:9], v[132:135], v[16:31]
	v_exp_f32_e32 v6, v125
	v_exp_f32_e32 v7, v109
	v_exp_f32_e32 v8, v126
	v_mov_b32_e32 v9, v119
	s_waitcnt lgkmcnt(0)
	v_mfma_f32_32x32x16_bf16 v[16:31], v[2:5], v[180:183], v[16:31]
	v_mov_b64_e32 v[2:3], s[60:61]
	v_mov_b64_e32 v[4:5], s[62:63]
	v_exp_f32_e32 v107, v110
	v_mov_b32_e32 v110, v120
	v_mfma_f32_32x32x16_bf16 v[80:95], v[2:5], v[140:143], v[80:95]
	v_exp_f32_e32 v108, v127
	v_exp_f32_e32 v109, v111
	v_cvt_pk_bf16_f32 v140, v14, v96
	v_cvt_pk_bf16_f32 v143, v115, v116
	v_mfma_f32_32x32x16_bf16 v[80:95], v[2:5], v[136:139], v[80:95]
	v_cvt_pk_bf16_f32 v128, v104, v105
	v_cvt_pk_bf16_f32 v141, v112, v113
	v_cvt_pk_bf16_f32 v136, v117, v13
	v_mfma_f32_32x32x16_bf16 v[80:95], v[2:5], v[132:135], v[80:95]
	v_cvt_pk_bf16_f32 v137, v9, v110
	v_cvt_pk_bf16_f32 v129, v106, v10
	v_cvt_pk_bf16_f32 v132, v15, v97
	v_cvt_pk_bf16_f32 v130, v12, v7
	v_mov_b32_e32 v7, v109
	v_cvt_pk_bf16_f32 v138, v11, v6
	v_mov_b32_e32 v6, v108
	v_cvt_pk_bf16_f32 v133, v98, v0
	v_cvt_pk_bf16_f32 v142, v99, v114
	v_mov_b32_e32 v0, v8
	v_mov_b32_e32 v8, v107
	v_cvt_pk_bf16_f32 v134, v100, v101
	v_cvt_pk_bf16_f32 v135, v102, v103
	v_cvt_pk_bf16_f32 v139, v0, v6
	v_cvt_pk_bf16_f32 v131, v8, v7
	v_mfma_f32_32x32x16_bf16 v[80:95], v[2:5], v[180:183], v[80:95]
	s_add_i32 s28, s28, 1
	s_add_i32 s13, s13, 1
	s_add_i32 s19, s19, 0x8000
	s_cmpk_eq_i32 s13, 0x45
	s_cbranch_scc1 .LBB0_464

.Lf_462:
	s_and_b32 s17, s19, 0x18000
	v_add_u32_e32 v0, s17, v227
	v_add_u32_e32 v2, v0, v228
	ds_read_b128 v[96:99], v2
	ds_read_b128 v[100:103], v2 offset:4096
	v_add_u32_e32 v2, v0, v226
	ds_read_b128 v[180:183], v2
	ds_read_b128 v[230:233], v2 offset:4096
	v_add_u32_e32 v2, v0, v225
	v_add_u32_e32 v0, v0, v224
	s_min_u32 s16, s28, 1
	ds_read_b128 v[234:237], v2
	ds_read_b128 v[238:241], v2 offset:4096
	ds_read_b128 v[242:245], v0
	ds_read_b128 v[246:249], v0 offset:4096
	s_lshl_b32 s16, s16, 15
	s_sub_i32 s16, s19, s16
	s_and_b32 s16, s16, 0x18000
	v_add_u32_e32 v0, s16, v195
	ds_read_b64_tr_b16 v[176:177], v0 offset:16384
	ds_read_b64_tr_b16 v[178:179], v0 offset:16896
	ds_read_b64_tr_b16 v[172:173], v0 offset:17408
	ds_read_b64_tr_b16 v[174:175], v0 offset:17920
	ds_read_b64_tr_b16 v[168:169], v0 offset:18432
	ds_read_b64_tr_b16 v[170:171], v0 offset:18944
	ds_read_b64_tr_b16 v[164:165], v0 offset:19456
	ds_read_b64_tr_b16 v[166:167], v0 offset:19968
	ds_read_b64_tr_b16 v[160:161], v0 offset:20480
	ds_read_b64_tr_b16 v[162:163], v0 offset:20992
	ds_read_b64_tr_b16 v[10:11], v0 offset:21504
	ds_read_b64_tr_b16 v[12:13], v0 offset:22016
	ds_read_b64_tr_b16 v[6:7], v0 offset:22528
	ds_read_b64_tr_b16 v[8:9], v0 offset:23040
	ds_read_b64_tr_b16 v[2:3], v0 offset:23552
	ds_read_b64_tr_b16 v[4:5], v0 offset:24064
	s_setprio 1
	s_waitcnt lgkmcnt(14)
	v_mfma_f32_32x32x16_bf16 v[112:127], v[96:99], v[156:159], 0
	v_mfma_f32_32x32x16_bf16 v[96:111], v[100:103], v[156:159], 0
	v_mfma_f32_32x32x16_bf16 v[112:127], v[180:183], v[152:155], v[112:127]
	v_mfma_f32_32x32x16_bf16 v[96:111], v[230:233], v[152:155], v[96:111]
	v_mfma_f32_32x32x16_bf16 v[112:127], v[234:237], v[148:151], v[112:127]
	v_mfma_f32_32x32x16_bf16 v[96:111], v[238:241], v[148:151], v[96:111]
	v_mfma_f32_32x32x16_bf16 v[112:127], v[242:245], v[144:147], v[112:127]
	v_mfma_f32_32x32x16_bf16 v[96:111], v[246:249], v[144:147], v[96:111]
	s_setprio 0
	v_max3_f32 v14, v112, v113, v114
	v_max3_f32 v15, v115, v116, v117
	v_max3_f32 v180, v118, v119, v120
	v_max3_f32 v181, v121, v122, v123
	v_max3_f32 v182, v124, v125, v126
	v_max3_f32 v183, v96, v97, v98
	v_max3_f32 v218, v99, v100, v101
	v_max3_f32 v219, v102, v103, v104
	s_nop 0
	v_max3_f32 v14, v14, v15, v180
	v_max3_f32 v220, v105, v106, v107
	v_max3_f32 v15, v181, v182, v127
	v_max3_f32 v221, v108, v109, v110
	s_xor_b64 s[30:31], s[4:5], -1
	v_max3_f32 v180, v183, v218, v219
	v_max3_f32 v181, v220, v221, v111
	s_nop 0
	v_max3_f32 v14, v14, v15, v180
	v_max_f32_e32 v14, v14, v181
	v_mov_b32_e32 v15, v14
	s_waitcnt lgkmcnt(0)
	s_nop 0
	v_permlane32_swap_b32_e32 v15, v14
	v_max_f32_e32 v14, v14, v15
	v_cmp_lt_f32_e32 vcc, 0x42800000, v14
	s_cbranch_vccz .Lf_459
	s_branch .Lf_to463

.LBB0_643:
	v_ashrrev_i32_e32 v189, 31, v188
	v_lshlrev_b64 v[218:219], 10, v[188:189]
	v_lshl_add_u64 v[218:219], v[218:219], 0, v[184:185]
	s_and_b64 s[10:11], s[10:11], exec
	s_cselect_b32 s63, s83, s88
	s_cselect_b32 s62, s68, s89
	v_lshlrev_b64 v[222:223], 2, v[218:219]
	v_lshl_add_u64 v[224:225], s[62:63], 0, v[222:223]
	global_load_dwordx4 v[234:237], v[224:225], off
	global_load_dwordx4 v[238:241], v[224:225], off offset:64
	global_load_dwordx4 v[242:245], v[224:225], off offset:512
	global_load_dwordx4 v[246:249], v[224:225], off offset:576
	s_waitcnt vmcnt(3)
	v_pk_add_f32 v[132:133], v[132:133], 1.0 op_sel_hi:[1,0]
	v_pk_add_f32 v[130:131], v[130:131], 1.0 op_sel_hi:[1,0]
	s_cselect_b32 s11, s73, s79
	s_cselect_b32 s10, s33, s78
	v_lshl_add_u64 v[222:223], s[10:11], 0, v[222:223]
	s_and_b64 vcc, exec, s[38:39]
	v_sub_f32_e32 v235, v235, v208
	v_sub_f32_e32 v234, v234, v208
	v_sub_f32_e32 v237, v237, v208
	v_sub_f32_e32 v236, v236, v208
	v_pk_mul_f32 v[236:237], v[194:195], v[236:237] op_sel_hi:[0,1]
	v_pk_mul_f32 v[234:235], v[194:195], v[234:235] op_sel_hi:[0,1]
	v_pk_fma_f32 v[234:235], v[158:159], v[234:235], v[162:163]
	v_pk_fma_f32 v[236:237], v[156:157], v[236:237], v[160:161]
	v_pk_fma_f32 v[126:127], v[126:127], v[130:131], v[234:235]
	v_pk_fma_f32 v[128:129], v[128:129], v[132:133], v[236:237]
	global_store_dwordx4 v[222:223], v[126:129], off
	s_nop 0
	s_nop 0
	v_pk_add_f32 v[126:127], v[136:137], 1.0 op_sel_hi:[1,0]
	v_pk_add_f32 v[128:129], v[134:135], 1.0 op_sel_hi:[1,0]
	s_waitcnt vmcnt(3)
	v_sub_f32_e32 v135, v239, v208
	v_sub_f32_e32 v134, v238, v208
	v_sub_f32_e32 v137, v241, v208
	v_sub_f32_e32 v136, v240, v208
	v_pk_mul_f32 v[136:137], v[194:195], v[136:137] op_sel_hi:[0,1]
	v_pk_mul_f32 v[134:135], v[194:195], v[134:135] op_sel_hi:[0,1]
	v_pk_fma_f32 v[134:135], v[152:153], v[134:135], v[154:155]
	v_pk_fma_f32 v[136:137], v[164:165], v[136:137], v[170:171]
	v_pk_fma_f32 v[122:123], v[122:123], v[128:129], v[134:135]
	v_pk_fma_f32 v[124:125], v[124:125], v[126:127], v[136:137]
	global_store_dwordx4 v[222:223], v[122:125], off offset:64
	s_nop 0
	s_waitcnt vmcnt(3)
	v_sub_f32_e32 v243, v243, v208
	v_sub_f32_e32 v242, v242, v208
	v_sub_f32_e32 v245, v245, v208
	v_sub_f32_e32 v244, v244, v208
	v_pk_mul_f32 v[244:245], v[194:195], v[244:245] op_sel_hi:[0,1]
	v_pk_mul_f32 v[242:243], v[194:195], v[242:243] op_sel_hi:[0,1]
	v_pk_add_f32 v[122:123], v[140:141], 1.0 op_sel_hi:[1,0]
	v_pk_add_f32 v[124:125], v[138:139], 1.0 op_sel_hi:[1,0]
	v_pk_fma_f32 v[242:243], v[174:175], v[242:243], v[178:179]
	v_pk_fma_f32 v[244:245], v[172:173], v[244:245], v[176:177]
	v_pk_fma_f32 v[118:119], v[118:119], v[124:125], v[242:243]
	v_pk_fma_f32 v[120:121], v[120:121], v[122:123], v[244:245]
	global_store_dwordx4 v[222:223], v[118:121], off offset:512
	s_nop 0
	s_waitcnt vmcnt(3)
	v_sub_f32_e32 v247, v247, v208
	v_sub_f32_e32 v246, v246, v208
	v_sub_f32_e32 v249, v249, v208
	v_sub_f32_e32 v248, v248, v208
	v_pk_mul_f32 v[248:249], v[194:195], v[248:249] op_sel_hi:[0,1]
	v_pk_mul_f32 v[246:247], v[194:195], v[246:247] op_sel_hi:[0,1]
	v_pk_add_f32 v[118:119], v[144:145], 1.0 op_sel_hi:[1,0]
	v_pk_add_f32 v[120:121], v[142:143], 1.0 op_sel_hi:[1,0]
	v_pk_fma_f32 v[246:247], v[166:167], v[246:247], v[168:169]
	v_pk_fma_f32 v[248:249], v[180:181], v[248:249], v[182:183]
	v_pk_fma_f32 v[114:115], v[114:115], v[120:121], v[246:247]
	v_pk_fma_f32 v[116:117], v[116:117], v[118:119], v[248:249]
	global_store_dwordx4 v[222:223], v[114:117], off offset:576
	s_cbranch_vccnz .LBB0_645
	s_nop 0
	v_or_b32_e32 v114, 16, v186
	v_ashrrev_i32_e32 v115, 31, v114
	v_lshl_add_u64 v[114:115], v[114:115], 3, s[6:7]
	global_load_dwordx2 v[190:191], v[114:115], off
	s_waitcnt vmcnt(0)
	v_mov_b32_e32 v192, v191
.LBB0_645:
	s_nop 0
	v_or_b32_e32 v114, 16, v188
	v_ashrrev_i32_e32 v115, 31, v114
	v_lshlrev_b64 v[114:115], 10, v[114:115]
	v_lshl_add_u64 v[114:115], v[114:115], 0, v[184:185]
	v_lshlrev_b64 v[134:135], 2, v[114:115]
	v_lshl_add_u64 v[136:137], s[62:63], 0, v[134:135]
	global_load_dwordx4 v[234:237], v[136:137], off
	global_load_dwordx4 v[238:241], v[136:137], off offset:64
	global_load_dwordx4 v[242:245], v[136:137], off offset:512
	global_load_dwordx4 v[246:249], v[136:137], off offset:576
	v_lshl_add_u64 v[134:135], s[10:11], 0, v[134:135]
	s_and_b64 vcc, exec, s[38:39]
	s_waitcnt vmcnt(3)
	v_sub_f32_e32 v235, v235, v190
	v_sub_f32_e32 v234, v234, v190
	v_sub_f32_e32 v237, v237, v190
	v_sub_f32_e32 v236, v236, v190
	v_pk_mul_f32 v[236:237], v[192:193], v[236:237] op_sel_hi:[0,1]
	v_pk_mul_f32 v[234:235], v[192:193], v[234:235] op_sel_hi:[0,1]
	v_pk_fma_f32 v[234:235], v[158:159], v[234:235], v[162:163]
	v_pk_fma_f32 v[236:237], v[156:157], v[236:237], v[160:161]
	v_pk_fma_f32 v[110:111], v[110:111], v[130:131], v[234:235]
	v_pk_fma_f32 v[112:113], v[112:113], v[132:133], v[236:237]
	global_store_dwordx4 v[134:135], v[110:113], off
	s_nop 0
	s_waitcnt vmcnt(3)
	v_sub_f32_e32 v239, v239, v190
	v_sub_f32_e32 v238, v238, v190
	v_sub_f32_e32 v241, v241, v190
	v_sub_f32_e32 v240, v240, v190
	v_pk_mul_f32 v[240:241], v[192:193], v[240:241] op_sel_hi:[0,1]
	v_pk_mul_f32 v[238:239], v[192:193], v[238:239] op_sel_hi:[0,1]
	v_pk_fma_f32 v[238:239], v[152:153], v[238:239], v[154:155]
	v_pk_fma_f32 v[240:241], v[164:165], v[240:241], v[170:171]
	v_pk_fma_f32 v[106:107], v[106:107], v[128:129], v[238:239]
	v_pk_fma_f32 v[108:109], v[108:109], v[126:127], v[240:241]
	global_store_dwordx4 v[134:135], v[106:109], off offset:64
	s_nop 0
	s_waitcnt vmcnt(3)
	v_sub_f32_e32 v243, v243, v190
	v_sub_f32_e32 v242, v242, v190
	v_sub_f32_e32 v245, v245, v190
	v_sub_f32_e32 v244, v244, v190
	v_pk_mul_f32 v[244:245], v[192:193], v[244:245] op_sel_hi:[0,1]
	v_pk_mul_f32 v[242:243], v[192:193], v[242:243] op_sel_hi:[0,1]
	v_pk_fma_f32 v[242:243], v[174:175], v[242:243], v[178:179]
	v_pk_fma_f32 v[244:245], v[172:173], v[244:245], v[176:177]
	v_pk_fma_f32 v[102:103], v[102:103], v[124:125], v[242:243]
	v_pk_fma_f32 v[104:105], v[104:105], v[122:123], v[244:245]
	global_store_dwordx4 v[134:135], v[102:105], off offset:512
	s_nop 0
	s_waitcnt vmcnt(3)
	v_sub_f32_e32 v249, v249, v190
	v_sub_f32_e32 v247, v247, v190
	v_sub_f32_e32 v246, v246, v190
	v_sub_f32_e32 v248, v248, v190
	v_pk_mul_f32 v[248:249], v[192:193], v[248:249] op_sel_hi:[0,1]
	v_pk_mul_f32 v[246:247], v[192:193], v[246:247] op_sel_hi:[0,1]
	v_pk_fma_f32 v[246:247], v[166:167], v[246:247], v[168:169]
	v_pk_fma_f32 v[248:249], v[180:181], v[248:249], v[182:183]
	v_pk_fma_f32 v[98:99], v[98:99], v[120:121], v[246:247]
	v_pk_fma_f32 v[100:101], v[100:101], v[118:119], v[248:249]
	global_store_dwordx4 v[134:135], v[98:101], off offset:576
	v_mov_b32_e32 v102, 1.0
	v_mov_b32_e32 v104, 0
	v_mov_b32_e32 v98, 0
	v_mov_b32_e32 v100, 1.0
	s_cbranch_vccnz .LBB0_647
	v_or_b32_e32 v100, 32, v186
	v_ashrrev_i32_e32 v101, 31, v100
	v_lshl_add_u64 v[100:101], v[100:101], 3, s[6:7]
	global_load_dwordx2 v[104:105], v[100:101], off
	s_waitcnt vmcnt(0)
	v_mov_b32_e32 v100, v105
.LBB0_647:
	v_or_b32_e32 v106, 32, v188
	v_ashrrev_i32_e32 v107, 31, v106
	v_lshlrev_b64 v[106:107], 10, v[106:107]
	v_lshl_add_u64 v[106:107], v[106:107], 0, v[184:185]
	v_lshlrev_b64 v[110:111], 2, v[106:107]
	v_lshl_add_u64 v[112:113], s[62:63], 0, v[110:111]
	global_load_dwordx4 v[234:237], v[112:113], off
	global_load_dwordx4 v[238:241], v[112:113], off offset:64
	global_load_dwordx4 v[242:245], v[112:113], off offset:512
	global_load_dwordx4 v[246:249], v[112:113], off offset:576
	v_lshl_add_u64 v[110:111], s[10:11], 0, v[110:111]
	s_and_b64 vcc, exec, s[38:39]
	s_waitcnt vmcnt(3)
	v_sub_f32_e32 v235, v235, v104
	v_sub_f32_e32 v234, v234, v104
	v_sub_f32_e32 v237, v237, v104
	v_sub_f32_e32 v236, v236, v104
	v_pk_mul_f32 v[236:237], v[100:101], v[236:237] op_sel_hi:[0,1]
	v_pk_mul_f32 v[234:235], v[100:101], v[234:235] op_sel_hi:[0,1]
	v_pk_fma_f32 v[234:235], v[158:159], v[234:235], v[162:163]
	v_pk_fma_f32 v[236:237], v[156:157], v[236:237], v[160:161]
	v_pk_fma_f32 v[94:95], v[94:95], v[130:131], v[234:235]
	v_pk_fma_f32 v[96:97], v[96:97], v[132:133], v[236:237]
	global_store_dwordx4 v[110:111], v[94:97], off
	s_nop 0
	s_waitcnt vmcnt(3)
	v_sub_f32_e32 v239, v239, v104
	v_sub_f32_e32 v238, v238, v104
	v_sub_f32_e32 v241, v241, v104
	v_sub_f32_e32 v240, v240, v104
	v_pk_mul_f32 v[240:241], v[100:101], v[240:241] op_sel_hi:[0,1]
	v_pk_mul_f32 v[238:239], v[100:101], v[238:239] op_sel_hi:[0,1]
	v_pk_fma_f32 v[238:239], v[152:153], v[238:239], v[154:155]
	v_pk_fma_f32 v[240:241], v[164:165], v[240:241], v[170:171]
	v_pk_fma_f32 v[90:91], v[90:91], v[128:129], v[238:239]
	v_pk_fma_f32 v[92:93], v[92:93], v[126:127], v[240:241]
	global_store_dwordx4 v[110:111], v[90:93], off offset:64
	s_nop 0
	s_waitcnt vmcnt(3)
	v_sub_f32_e32 v243, v243, v104
	v_sub_f32_e32 v242, v242, v104
	v_sub_f32_e32 v245, v245, v104
	v_sub_f32_e32 v244, v244, v104
	v_pk_mul_f32 v[244:245], v[100:101], v[244:245] op_sel_hi:[0,1]
	v_pk_mul_f32 v[242:243], v[100:101], v[242:243] op_sel_hi:[0,1]
	v_pk_fma_f32 v[242:243], v[174:175], v[242:243], v[178:179]
	v_pk_fma_f32 v[244:245], v[172:173], v[244:245], v[176:177]
	v_pk_fma_f32 v[86:87], v[86:87], v[124:125], v[242:243]
	v_pk_fma_f32 v[88:89], v[88:89], v[122:123], v[244:245]
	global_store_dwordx4 v[110:111], v[86:89], off offset:512
	s_nop 0
	s_waitcnt vmcnt(3)
	v_sub_f32_e32 v247, v247, v104
	v_sub_f32_e32 v246, v246, v104
	v_sub_f32_e32 v249, v249, v104
	v_sub_f32_e32 v248, v248, v104
	v_pk_mul_f32 v[248:249], v[100:101], v[248:249] op_sel_hi:[0,1]
	v_pk_mul_f32 v[246:247], v[100:101], v[246:247] op_sel_hi:[0,1]
	v_pk_fma_f32 v[246:247], v[166:167], v[246:247], v[168:169]
	v_pk_fma_f32 v[248:249], v[180:181], v[248:249], v[182:183]
	v_pk_fma_f32 v[82:83], v[82:83], v[120:121], v[246:247]
	v_pk_fma_f32 v[84:85], v[84:85], v[118:119], v[248:249]
	global_store_dwordx4 v[110:111], v[82:85], off offset:576
	s_cbranch_vccnz .LBB0_649
	s_nop 0
	v_or_b32_e32 v82, 48, v186
	v_ashrrev_i32_e32 v83, 31, v82
	v_lshl_add_u64 v[82:83], v[82:83], 3, s[6:7]
	global_load_dwordx2 v[98:99], v[82:83], off
	s_waitcnt vmcnt(0)
	v_mov_b32_e32 v102, v99
.LBB0_649:
	s_nop 0
	v_or_b32_e32 v82, 48, v188
	v_ashrrev_i32_e32 v83, 31, v82
	v_lshlrev_b64 v[82:83], 10, v[82:83]
	v_lshl_add_u64 v[82:83], v[82:83], 0, v[184:185]
	v_lshlrev_b64 v[86:87], 2, v[82:83]
	v_lshl_add_u64 v[88:89], s[62:63], 0, v[86:87]
	global_load_dwordx4 v[234:237], v[88:89], off
	global_load_dwordx4 v[238:241], v[88:89], off offset:64
	global_load_dwordx4 v[242:245], v[88:89], off offset:512
	global_load_dwordx4 v[246:249], v[88:89], off offset:576
	v_lshl_add_u64 v[86:87], s[10:11], 0, v[86:87]
	s_and_b64 vcc, exec, s[38:39]
	s_waitcnt vmcnt(3)
	v_sub_f32_e32 v235, v235, v98
	v_sub_f32_e32 v234, v234, v98
	v_sub_f32_e32 v237, v237, v98
	v_sub_f32_e32 v236, v236, v98
	v_pk_mul_f32 v[236:237], v[102:103], v[236:237] op_sel_hi:[0,1]
	v_pk_mul_f32 v[234:235], v[102:103], v[234:235] op_sel_hi:[0,1]
	v_pk_fma_f32 v[234:235], v[158:159], v[234:235], v[162:163]
	v_pk_fma_f32 v[236:237], v[156:157], v[236:237], v[160:161]
	v_pk_fma_f32 v[78:79], v[78:79], v[130:131], v[234:235]
	v_pk_fma_f32 v[80:81], v[80:81], v[132:133], v[236:237]
	global_store_dwordx4 v[86:87], v[78:81], off
	s_nop 0
	s_waitcnt vmcnt(3)
	v_sub_f32_e32 v239, v239, v98
	v_sub_f32_e32 v238, v238, v98
	v_sub_f32_e32 v241, v241, v98
	v_sub_f32_e32 v240, v240, v98
	v_pk_mul_f32 v[240:241], v[102:103], v[240:241] op_sel_hi:[0,1]
	v_pk_mul_f32 v[238:239], v[102:103], v[238:239] op_sel_hi:[0,1]
	v_pk_fma_f32 v[238:239], v[152:153], v[238:239], v[154:155]
	v_pk_fma_f32 v[240:241], v[164:165], v[240:241], v[170:171]
	v_pk_fma_f32 v[74:75], v[74:75], v[128:129], v[238:239]
	v_pk_fma_f32 v[76:77], v[76:77], v[126:127], v[240:241]
	global_store_dwordx4 v[86:87], v[74:77], off offset:64
	s_nop 0
	s_waitcnt vmcnt(3)
	v_sub_f32_e32 v243, v243, v98
	v_sub_f32_e32 v242, v242, v98
	v_sub_f32_e32 v245, v245, v98
	v_sub_f32_e32 v244, v244, v98
	v_pk_mul_f32 v[244:245], v[102:103], v[244:245] op_sel_hi:[0,1]
	v_pk_mul_f32 v[242:243], v[102:103], v[242:243] op_sel_hi:[0,1]
	v_pk_fma_f32 v[242:243], v[174:175], v[242:243], v[178:179]
	v_pk_fma_f32 v[244:245], v[172:173], v[244:245], v[176:177]
	v_pk_fma_f32 v[70:71], v[70:71], v[124:125], v[242:243]
	v_pk_fma_f32 v[72:73], v[72:73], v[122:123], v[244:245]
	global_store_dwordx4 v[86:87], v[70:73], off offset:512
	s_nop 0
	s_waitcnt vmcnt(3)
	v_sub_f32_e32 v249, v249, v98
	v_sub_f32_e32 v247, v247, v98
	v_sub_f32_e32 v246, v246, v98
	v_sub_f32_e32 v248, v248, v98
	v_pk_mul_f32 v[248:249], v[102:103], v[248:249] op_sel_hi:[0,1]
	v_pk_mul_f32 v[246:247], v[102:103], v[246:247] op_sel_hi:[0,1]
	v_pk_fma_f32 v[246:247], v[166:167], v[246:247], v[168:169]
	v_pk_fma_f32 v[248:249], v[180:181], v[248:249], v[182:183]
	v_pk_fma_f32 v[66:67], v[66:67], v[120:121], v[246:247]
	v_pk_fma_f32 v[68:69], v[68:69], v[118:119], v[248:249]
	global_store_dwordx4 v[86:87], v[66:69], off offset:576
	v_mov_b32_e32 v70, 1.0
	v_mov_b32_e32 v74, 0
	v_mov_b32_e32 v66, 0
	v_mov_b32_e32 v72, 1.0
	s_cbranch_vccnz .LBB0_651
	v_lshl_add_u64 v[68:69], v[186:187], 3, s[6:7]
	global_load_dwordx2 v[74:75], v[68:69], off offset:1024
	s_waitcnt vmcnt(0)
	v_mov_b32_e32 v72, v75
.LBB0_651:
	v_lshlrev_b64 v[68:69], 10, v[188:189]
	v_lshl_add_u64 v[68:69], v[68:69], 0, v[184:185]
	v_lshl_add_u64 v[80:81], v[68:69], 2, v[200:201]
	v_lshl_add_u64 v[82:83], s[62:63], 0, v[80:81]
	global_load_dwordx4 v[234:237], v[82:83], off
	global_load_dwordx4 v[238:241], v[82:83], off offset:64
	global_load_dwordx4 v[242:245], v[82:83], off offset:512
	global_load_dwordx4 v[246:249], v[82:83], off offset:576
	v_lshl_add_u64 v[80:81], s[10:11], 0, v[80:81]
	s_and_b64 vcc, exec, s[38:39]
	s_waitcnt vmcnt(3)
	v_sub_f32_e32 v235, v235, v74
	v_sub_f32_e32 v234, v234, v74
	v_sub_f32_e32 v237, v237, v74
	v_sub_f32_e32 v236, v236, v74
	v_pk_mul_f32 v[236:237], v[72:73], v[236:237] op_sel_hi:[0,1]
	v_pk_mul_f32 v[234:235], v[72:73], v[234:235] op_sel_hi:[0,1]
	v_pk_fma_f32 v[234:235], v[158:159], v[234:235], v[162:163]
	v_pk_fma_f32 v[236:237], v[156:157], v[236:237], v[160:161]
	v_pk_fma_f32 v[62:63], v[62:63], v[130:131], v[234:235]
	v_pk_fma_f32 v[64:65], v[64:65], v[132:133], v[236:237]
	global_store_dwordx4 v[80:81], v[62:65], off
	s_nop 0
	s_waitcnt vmcnt(3)
	v_sub_f32_e32 v239, v239, v74
	v_sub_f32_e32 v238, v238, v74
	v_sub_f32_e32 v241, v241, v74
	v_sub_f32_e32 v240, v240, v74
	v_pk_mul_f32 v[240:241], v[72:73], v[240:241] op_sel_hi:[0,1]
	v_pk_mul_f32 v[238:239], v[72:73], v[238:239] op_sel_hi:[0,1]
	v_pk_fma_f32 v[238:239], v[152:153], v[238:239], v[154:155]
	v_pk_fma_f32 v[240:241], v[164:165], v[240:241], v[170:171]
	v_pk_fma_f32 v[58:59], v[58:59], v[128:129], v[238:239]
	v_pk_fma_f32 v[60:61], v[60:61], v[126:127], v[240:241]
	global_store_dwordx4 v[80:81], v[58:61], off offset:64
	s_nop 0
	s_waitcnt vmcnt(3)
	v_sub_f32_e32 v243, v243, v74
	v_sub_f32_e32 v242, v242, v74
	v_sub_f32_e32 v245, v245, v74
	v_sub_f32_e32 v244, v244, v74
	v_pk_mul_f32 v[244:245], v[72:73], v[244:245] op_sel_hi:[0,1]
	v_pk_mul_f32 v[242:243], v[72:73], v[242:243] op_sel_hi:[0,1]
	v_pk_fma_f32 v[242:243], v[174:175], v[242:243], v[178:179]
	v_pk_fma_f32 v[244:245], v[172:173], v[244:245], v[176:177]
	v_pk_fma_f32 v[54:55], v[54:55], v[124:125], v[242:243]
	v_pk_fma_f32 v[56:57], v[56:57], v[122:123], v[244:245]
	global_store_dwordx4 v[80:81], v[54:57], off offset:512
	s_nop 0
	s_waitcnt vmcnt(3)
	v_sub_f32_e32 v247, v247, v74
	v_sub_f32_e32 v246, v246, v74
	v_sub_f32_e32 v249, v249, v74
	v_sub_f32_e32 v248, v248, v74
	v_pk_mul_f32 v[248:249], v[72:73], v[248:249] op_sel_hi:[0,1]
	v_pk_mul_f32 v[246:247], v[72:73], v[246:247] op_sel_hi:[0,1]
	v_pk_fma_f32 v[246:247], v[166:167], v[246:247], v[168:169]
	v_pk_fma_f32 v[248:249], v[180:181], v[248:249], v[182:183]
	v_pk_fma_f32 v[50:51], v[50:51], v[120:121], v[246:247]
	v_pk_fma_f32 v[52:53], v[52:53], v[118:119], v[248:249]
	global_store_dwordx4 v[80:81], v[50:53], off offset:576
	s_cbranch_vccnz .LBB0_653
	s_nop 0
	v_lshl_add_u64 v[50:51], v[186:187], 3, s[6:7]
	global_load_dwordx2 v[66:67], v[50:51], off offset:1152
	s_waitcnt vmcnt(0)
	v_mov_b32_e32 v70, v67
.LBB0_653:
	v_lshl_add_u64 v[54:55], v[68:69], 2, v[202:203]
	v_lshl_add_u64 v[56:57], s[62:63], 0, v[54:55]
	global_load_dwordx4 v[234:237], v[56:57], off
	global_load_dwordx4 v[238:241], v[56:57], off offset:64
	global_load_dwordx4 v[242:245], v[56:57], off offset:512
	global_load_dwordx4 v[246:249], v[56:57], off offset:576
	v_lshl_add_u64 v[54:55], s[10:11], 0, v[54:55]
	s_and_b64 vcc, exec, s[38:39]
	s_waitcnt vmcnt(3)
	v_sub_f32_e32 v235, v235, v66
	v_sub_f32_e32 v234, v234, v66
	v_sub_f32_e32 v237, v237, v66
	v_sub_f32_e32 v236, v236, v66
	v_pk_mul_f32 v[236:237], v[70:71], v[236:237] op_sel_hi:[0,1]
	v_pk_mul_f32 v[234:235], v[70:71], v[234:235] op_sel_hi:[0,1]
	v_pk_fma_f32 v[234:235], v[158:159], v[234:235], v[162:163]
	v_pk_fma_f32 v[236:237], v[156:157], v[236:237], v[160:161]
	v_pk_fma_f32 v[46:47], v[46:47], v[130:131], v[234:235]
	v_pk_fma_f32 v[48:49], v[48:49], v[132:133], v[236:237]
	global_store_dwordx4 v[54:55], v[46:49], off
	s_nop 0
	s_waitcnt vmcnt(3)
	v_sub_f32_e32 v239, v239, v66
	v_sub_f32_e32 v238, v238, v66
	v_sub_f32_e32 v241, v241, v66
	v_sub_f32_e32 v240, v240, v66
	v_pk_mul_f32 v[240:241], v[70:71], v[240:241] op_sel_hi:[0,1]
	v_pk_mul_f32 v[238:239], v[70:71], v[238:239] op_sel_hi:[0,1]
	v_pk_fma_f32 v[238:239], v[152:153], v[238:239], v[154:155]
	v_pk_fma_f32 v[240:241], v[164:165], v[240:241], v[170:171]
	v_pk_fma_f32 v[42:43], v[42:43], v[128:129], v[238:239]
	v_pk_fma_f32 v[44:45], v[44:45], v[126:127], v[240:241]
	global_store_dwordx4 v[54:55], v[42:45], off offset:64
	s_nop 0
	s_waitcnt vmcnt(3)
	v_sub_f32_e32 v243, v243, v66
	v_sub_f32_e32 v242, v242, v66
	v_sub_f32_e32 v245, v245, v66
	v_sub_f32_e32 v244, v244, v66
	v_pk_mul_f32 v[244:245], v[70:71], v[244:245] op_sel_hi:[0,1]
	v_pk_mul_f32 v[242:243], v[70:71], v[242:243] op_sel_hi:[0,1]
	v_pk_fma_f32 v[242:243], v[174:175], v[242:243], v[178:179]
	v_pk_fma_f32 v[244:245], v[172:173], v[244:245], v[176:177]
	v_pk_fma_f32 v[38:39], v[38:39], v[124:125], v[242:243]
	v_pk_fma_f32 v[40:41], v[40:41], v[122:123], v[244:245]
	global_store_dwordx4 v[54:55], v[38:41], off offset:512
	s_nop 0
	s_waitcnt vmcnt(3)
	v_sub_f32_e32 v249, v249, v66
	v_sub_f32_e32 v247, v247, v66
	v_sub_f32_e32 v246, v246, v66
	v_sub_f32_e32 v248, v248, v66
	v_pk_mul_f32 v[248:249], v[70:71], v[248:249] op_sel_hi:[0,1]
	v_pk_mul_f32 v[246:247], v[70:71], v[246:247] op_sel_hi:[0,1]
	v_pk_fma_f32 v[246:247], v[166:167], v[246:247], v[168:169]
	v_pk_fma_f32 v[248:249], v[180:181], v[248:249], v[182:183]
	v_pk_fma_f32 v[34:35], v[34:35], v[120:121], v[246:247]
	v_pk_fma_f32 v[36:37], v[36:37], v[118:119], v[248:249]
	global_store_dwordx4 v[54:55], v[34:37], off offset:576
	v_mov_b32_e32 v38, 1.0
	v_mov_b32_e32 v42, 0
	v_mov_b32_e32 v34, 0
	v_mov_b32_e32 v40, 1.0
	s_cbranch_vccnz .LBB0_655
	v_lshl_add_u64 v[36:37], v[186:187], 3, s[6:7]
	global_load_dwordx2 v[42:43], v[36:37], off offset:1280
	s_waitcnt vmcnt(0)
	v_mov_b32_e32 v40, v43
.LBB0_655:
	v_lshlrev_b64 v[36:37], 10, v[188:189]
	v_lshl_add_u64 v[36:37], v[36:37], 0, v[184:185]
	v_lshl_add_u64 v[48:49], v[36:37], 2, v[204:205]
	v_lshl_add_u64 v[50:51], s[62:63], 0, v[48:49]
	global_load_dwordx4 v[234:237], v[50:51], off
	global_load_dwordx4 v[238:241], v[50:51], off offset:64
	global_load_dwordx4 v[242:245], v[50:51], off offset:512
	global_load_dwordx4 v[246:249], v[50:51], off offset:576
	v_lshl_add_u64 v[48:49], s[10:11], 0, v[48:49]
	s_and_b64 vcc, exec, s[38:39]
	s_waitcnt vmcnt(3)
	v_sub_f32_e32 v235, v235, v42
	v_sub_f32_e32 v234, v234, v42
	v_sub_f32_e32 v237, v237, v42
	v_sub_f32_e32 v236, v236, v42
	v_pk_mul_f32 v[236:237], v[40:41], v[236:237] op_sel_hi:[0,1]
	v_pk_mul_f32 v[234:235], v[40:41], v[234:235] op_sel_hi:[0,1]
	v_pk_fma_f32 v[234:235], v[158:159], v[234:235], v[162:163]
	v_pk_fma_f32 v[236:237], v[156:157], v[236:237], v[160:161]
	v_pk_fma_f32 v[30:31], v[30:31], v[130:131], v[234:235]
	v_pk_fma_f32 v[32:33], v[32:33], v[132:133], v[236:237]
	global_store_dwordx4 v[48:49], v[30:33], off
	s_nop 0
	s_waitcnt vmcnt(3)
	v_sub_f32_e32 v239, v239, v42
	v_sub_f32_e32 v238, v238, v42
	v_sub_f32_e32 v241, v241, v42
	v_sub_f32_e32 v240, v240, v42
	v_pk_mul_f32 v[240:241], v[40:41], v[240:241] op_sel_hi:[0,1]
	v_pk_mul_f32 v[238:239], v[40:41], v[238:239] op_sel_hi:[0,1]
	v_pk_fma_f32 v[238:239], v[152:153], v[238:239], v[154:155]
	v_pk_fma_f32 v[240:241], v[164:165], v[240:241], v[170:171]
	v_pk_fma_f32 v[26:27], v[26:27], v[128:129], v[238:239]
	v_pk_fma_f32 v[28:29], v[28:29], v[126:127], v[240:241]
	global_store_dwordx4 v[48:49], v[26:29], off offset:64
	s_nop 0
	s_waitcnt vmcnt(3)
	v_sub_f32_e32 v243, v243, v42
	v_sub_f32_e32 v242, v242, v42
	v_sub_f32_e32 v245, v245, v42
	v_sub_f32_e32 v244, v244, v42
	v_pk_mul_f32 v[244:245], v[40:41], v[244:245] op_sel_hi:[0,1]
	v_pk_mul_f32 v[242:243], v[40:41], v[242:243] op_sel_hi:[0,1]
	v_pk_fma_f32 v[242:243], v[174:175], v[242:243], v[178:179]
	v_pk_fma_f32 v[244:245], v[172:173], v[244:245], v[176:177]
	v_pk_fma_f32 v[22:23], v[22:23], v[124:125], v[242:243]
	v_pk_fma_f32 v[24:25], v[24:25], v[122:123], v[244:245]
	global_store_dwordx4 v[48:49], v[22:25], off offset:512
	s_nop 0
	s_waitcnt vmcnt(3)
	v_sub_f32_e32 v247, v247, v42
	v_sub_f32_e32 v246, v246, v42
	v_sub_f32_e32 v249, v249, v42
	v_sub_f32_e32 v248, v248, v42
	v_pk_mul_f32 v[248:249], v[40:41], v[248:249] op_sel_hi:[0,1]
	v_pk_mul_f32 v[246:247], v[40:41], v[246:247] op_sel_hi:[0,1]
	v_pk_fma_f32 v[246:247], v[166:167], v[246:247], v[168:169]
	v_pk_fma_f32 v[248:249], v[180:181], v[248:249], v[182:183]
	v_pk_fma_f32 v[18:19], v[18:19], v[120:121], v[246:247]
	v_pk_fma_f32 v[20:21], v[20:21], v[118:119], v[248:249]
	global_store_dwordx4 v[48:49], v[18:21], off offset:576
	s_cbranch_vccnz .LBB0_657
	s_nop 0
	v_lshl_add_u64 v[18:19], v[186:187], 3, s[6:7]
	global_load_dwordx2 v[34:35], v[18:19], off offset:1408
	s_waitcnt vmcnt(0)
	v_mov_b32_e32 v38, v35
.LBB0_657:
	v_lshl_add_u64 v[22:23], v[36:37], 2, v[206:207]
	v_lshl_add_u64 v[24:25], s[62:63], 0, v[22:23]
	global_load_dwordx4 v[234:237], v[24:25], off
	global_load_dwordx4 v[238:241], v[24:25], off offset:64
	global_load_dwordx4 v[242:245], v[24:25], off offset:512
	global_load_dwordx4 v[246:249], v[24:25], off offset:576
	v_lshl_add_u64 v[22:23], s[10:11], 0, v[22:23]
	s_andn2_b64 vcc, exec, s[36:37]
	s_mov_b64 s[10:11], -1
	s_waitcnt vmcnt(3)
	v_sub_f32_e32 v235, v235, v34
	v_sub_f32_e32 v234, v234, v34
	v_sub_f32_e32 v237, v237, v34
	v_sub_f32_e32 v236, v236, v34
	v_pk_mul_f32 v[236:237], v[38:39], v[236:237] op_sel_hi:[0,1]
	v_pk_mul_f32 v[234:235], v[38:39], v[234:235] op_sel_hi:[0,1]
	v_pk_fma_f32 v[234:235], v[158:159], v[234:235], v[162:163]
	v_pk_fma_f32 v[236:237], v[156:157], v[236:237], v[160:161]
	v_pk_fma_f32 v[14:15], v[14:15], v[130:131], v[234:235]
	v_pk_fma_f32 v[16:17], v[16:17], v[132:133], v[236:237]
	global_store_dwordx4 v[22:23], v[14:17], off
	s_nop 0
	s_waitcnt vmcnt(3)
	v_sub_f32_e32 v239, v239, v34
	v_sub_f32_e32 v238, v238, v34
	v_sub_f32_e32 v241, v241, v34
	v_sub_f32_e32 v240, v240, v34
	v_pk_mul_f32 v[240:241], v[38:39], v[240:241] op_sel_hi:[0,1]
	v_pk_mul_f32 v[238:239], v[38:39], v[238:239] op_sel_hi:[0,1]
	v_pk_fma_f32 v[238:239], v[152:153], v[238:239], v[154:155]
	v_pk_fma_f32 v[240:241], v[164:165], v[240:241], v[170:171]
	v_pk_fma_f32 v[10:11], v[10:11], v[128:129], v[238:239]
	v_pk_fma_f32 v[12:13], v[12:13], v[126:127], v[240:241]
	global_store_dwordx4 v[22:23], v[10:13], off offset:64
	s_nop 0
	s_waitcnt vmcnt(3)
	v_sub_f32_e32 v243, v243, v34
	v_sub_f32_e32 v242, v242, v34
	v_sub_f32_e32 v245, v245, v34
	v_sub_f32_e32 v244, v244, v34
	v_pk_mul_f32 v[244:245], v[38:39], v[244:245] op_sel_hi:[0,1]
	v_pk_mul_f32 v[242:243], v[38:39], v[242:243] op_sel_hi:[0,1]
	v_pk_fma_f32 v[242:243], v[174:175], v[242:243], v[178:179]
	v_pk_fma_f32 v[244:245], v[172:173], v[244:245], v[176:177]
	v_pk_fma_f32 v[6:7], v[6:7], v[124:125], v[242:243]
	v_pk_fma_f32 v[8:9], v[8:9], v[122:123], v[244:245]
	global_store_dwordx4 v[22:23], v[6:9], off offset:512
	s_nop 0
	s_waitcnt vmcnt(3)
	v_sub_f32_e32 v247, v247, v34
	v_sub_f32_e32 v246, v246, v34
	v_sub_f32_e32 v249, v249, v34
	v_sub_f32_e32 v248, v248, v34
	v_pk_mul_f32 v[248:249], v[38:39], v[248:249] op_sel_hi:[0,1]
	v_pk_mul_f32 v[246:247], v[38:39], v[246:247] op_sel_hi:[0,1]
	v_pk_fma_f32 v[246:247], v[166:167], v[246:247], v[168:169]
	v_pk_fma_f32 v[248:249], v[180:181], v[248:249], v[182:183]
	v_pk_fma_f32 v[2:3], v[2:3], v[120:121], v[246:247]
	v_pk_fma_f32 v[4:5], v[4:5], v[118:119], v[248:249]
	global_store_dwordx4 v[22:23], v[2:5], off offset:576
	s_cbranch_vccnz .LBB0_626
	s_andn2_b64 vcc, exec, s[4:5]
	s_cbranch_vccnz .LBB0_625
	s_barrier
	s_branch .LBB0_625
